# attention phase: static s_setprio 1 for waves 0-3 (older half) on top of the rewritten FFN-up epilogue
# baseline (speedup 1.0000x reference)
; #define LAS __attribute__((address_space(3)))
; __global__ void __launch_bounds__(NTHREADS, 2) mega_fwd(Args args) {
;     ...
;                 {
;                     AttnP P{QKB, VT, OB, FG, args.in[2] + l * 6, args.in[7] + l * 64, (const float*)ctl + 1024 + l, args.lam_init[l]};
;                     volatile LAS unsigned* nxt = (volatile LAS unsigned*)(lds + MISC_OFF);
;     ...
;                   for (int rep = 0; rep < 2; ++rep) { if (rep) { xcd_barrier(xbar); if (bx == 0 && tid == 0) ctl[64 * l] = 0u; xcd_barrier(xbar); }
;     ...
;                     const int xq = bx & 7;
;                     for (;;) {
;                         if (tid == 0) nxt[0] = atomicAdd(ctl + 64 * l + 8 * (xq + 1), 1u);
;                         __syncthreads();
;                         const unsigned u = nxt[0];
;                         __syncthreads();
;                         if (u >= 256u) break;
;                         const int jj = (int)(u & 63u), qb = 15 - (jj >> 2), rem = xq + 8 * (4 * (int)(u >> 6) + (jj & 3));
.LBB0_620:
	s_or_b64 exec, exec, s[0:1]
	v_readlane_b32 s0, v251, 11
	v_readlane_b32 s1, v251, 12
	s_waitcnt lgkmcnt(0)
	s_barrier
	s_load_dword s0, s[0:1], 0xa8
	s_waitcnt lgkmcnt(0)
	v_sub_f32_e64 v212, 1.0, s0
	v_readfirstlane_b32 s2, v240
	s_cmp_lt_u32 s2, 0x100
	s_cbranch_scc0 .Lprio_skip
	s_setprio 1
